# v56 + residual-add epilogue: the 32 residual loads hoisted into spare VGPR buffers (4 row-groups in flight), counted vmcnt waits
# baseline (speedup 1.0000x reference)
.LBB0_234:
	s_lshl_b32 s29, s54, 8
	v_mov_b32_e32 v140, v144
	v_mov_b32_e32 v166, v145
	s_add_i32 s29, s29, s62
	v_readlane_b32 s50, v235, 13
	v_add_u32_e32 v142, s29, v140
	s_lshl_b32 s29, s28, 8
	s_or_b32 s29, s29, s63
	v_lshl_add_u32 v140, v166, 3, s29
	v_ashrrev_i32_e32 v143, 31, v142
	v_ashrrev_i32_e32 v141, 31, v140
	v_lshlrev_b64 v[148:149], 10, v[142:143]
	v_lshl_add_u64 v[156:157], v[148:149], 0, v[140:141]
	v_lshlrev_b64 v[158:159], 2, v[156:157]
	v_readlane_b32 s51, v235, 14
	v_lshl_add_u64 v[162:163], v[156:157], 1, s[22:23]
	v_lshl_add_u64 v[164:165], s[70:71], 0, v[158:159]
	v_lshl_add_u64 v[160:161], s[50:51], 0, v[158:159]
	v_mov_b32_e32 v184, v160
	v_mov_b32_e32 v185, v161
	v_mov_b32_e32 v186, 0x10000
	v_mov_b32_e32 v187, 0
	v_mov_b32_e32 v188, 0x50000
	v_mov_b32_e32 v189, 0
	global_load_dwordx4 v[168:171], v[184:185], off
	global_load_dwordx4 v[172:175], v[184:185], off offset:16
	global_load_dwordx4 v[176:179], v[184:185], off offset:512
	global_load_dwordx4 v[180:183], v[184:185], off offset:528
	v_lshl_add_u64 v[184:185], v[184:185], 0, v[186:187]
	global_load_dwordx4 v[200:203], v[184:185], off
	global_load_dwordx4 v[204:207], v[184:185], off offset:16
	global_load_dwordx4 v[208:211], v[184:185], off offset:512
	global_load_dwordx4 v[212:215], v[184:185], off offset:528
	v_lshl_add_u64 v[184:185], v[184:185], 0, v[186:187]
	global_load_dwordx4 v[216:219], v[184:185], off
	global_load_dwordx4 v[220:223], v[184:185], off offset:16
	global_load_dwordx4 v[224:227], v[184:185], off offset:512
	global_load_dwordx4 v[228:231], v[184:185], off offset:528
	v_lshl_add_u64 v[184:185], v[184:185], 0, v[186:187]
	global_load_dwordx4 v[238:241], v[184:185], off
	global_load_dwordx4 v[242:245], v[184:185], off offset:16
	global_load_dwordx4 v[246:249], v[184:185], off offset:512
	global_load_dwordx4 v[250:253], v[184:185], off offset:528
	s_nop 0
	s_nop 0
	s_lshl_b32 s54, s28, 2
	s_ashr_i32 s55, s54, 31
	s_waitcnt vmcnt(14)
	v_pk_add_f32 v[150:151], v[124:125], v[170:171]
	v_pk_add_f32 v[148:149], v[122:123], v[168:169]
	v_pk_add_f32 v[128:129], v[128:129], v[174:175]
	v_pk_add_f32 v[126:127], v[126:127], v[172:173]
	v_cvt_pk_bf16_f32 v122, v148, v149
	v_cvt_pk_bf16_f32 v123, v150, v151
	v_cvt_pk_bf16_f32 v124, v126, v127
	v_cvt_pk_bf16_f32 v125, v128, v129
	global_store_dwordx4 v[164:165], v[148:151], off
	global_store_dwordx4 v[164:165], v[126:129], off offset:16
	global_store_dwordx4 v[162:163], v[122:125], off
	s_nop 0
	s_nop 0
	v_and_b32_e32 v123, 64, v192
	v_xor_b32_e32 v122, 16, v192
	v_add_u32_e32 v123, 64, v123
	v_xor_b32_e32 v124, 32, v192
	v_cmp_lt_i32_e32 vcc, v122, v123
	v_mul_f32_e32 v125, v151, v151
	v_mul_f32_e32 v127, v127, v127
	v_cndmask_b32_e32 v122, v192, v122, vcc
	v_cmp_lt_i32_e32 vcc, v124, v123
	v_lshlrev_b32_e32 v123, 2, v122
	v_mul_f32_e32 v129, v129, v129
	v_cndmask_b32_e32 v124, v192, v124, vcc
	v_lshlrev_b32_e32 v122, 2, v124
	v_mul_f32_e32 v124, v149, v149
	v_fmac_f32_e32 v124, v148, v148
	v_fmac_f32_e32 v125, v150, v150
	v_fmac_f32_e32 v127, v126, v126
	v_fmac_f32_e32 v129, v128, v128
	v_add_f32_e32 v124, v124, v125
	v_add_f32_e32 v125, v127, v129
	v_add_f32_e32 v128, v125, v124
	v_cmp_eq_u32_e32 vcc, 0, v166
	s_waitcnt vmcnt(15)
	v_pk_add_f32 v[120:121], v[120:121], v[178:179]
	v_pk_add_f32 v[118:119], v[118:119], v[176:177]
	v_pk_add_f32 v[126:127], v[116:117], v[182:183]
	v_pk_add_f32 v[124:125], v[114:115], v[180:181]
	v_mul_f32_e32 v114, v119, v119
	v_mul_f32_e32 v115, v121, v121
	v_mul_f32_e32 v116, v125, v125
	v_mul_f32_e32 v117, v127, v127
	v_fmac_f32_e32 v114, v118, v118
	v_fmac_f32_e32 v115, v120, v120
	v_fmac_f32_e32 v116, v124, v124
	v_fmac_f32_e32 v117, v126, v126
	v_add_f32_e32 v114, v114, v115
	v_add_f32_e32 v115, v116, v117
	v_add_f32_e32 v114, v115, v114
	v_add_f32_e32 v114, v128, v114
	ds_bpermute_b32 v115, v123, v114
	global_store_dwordx4 v[164:165], v[118:121], off offset:512
	global_store_dwordx4 v[164:165], v[124:127], off offset:528
	v_cvt_pk_bf16_f32 v116, v118, v119
	v_cvt_pk_bf16_f32 v117, v120, v121
	v_cvt_pk_bf16_f32 v118, v124, v125
	s_waitcnt lgkmcnt(0)
	v_add_f32_e32 v114, v114, v115
	ds_bpermute_b32 v115, v122, v114
	v_cvt_pk_bf16_f32 v119, v126, v127
	global_store_dwordx4 v[162:163], v[116:119], off offset:256
	s_and_saveexec_b64 s[50:51], vcc
	s_cbranch_execz .LBB0_236
	v_readlane_b32 s28, v235, 1
	v_lshlrev_b64 v[116:117], 6, v[142:143]
	v_readlane_b32 s29, v235, 2
	s_lshl_b32 s78, s60, 2
	s_waitcnt lgkmcnt(0)
	v_add_f32_e32 v114, v114, v115
	v_lshl_add_u64 v[116:117], s[28:29], 0, v[116:117]
	v_lshl_add_u64 v[116:117], s[54:55], 2, v[116:117]
	v_lshl_add_u64 v[116:117], v[116:117], 0, s[78:79]
	s_mov_b32 s78, s76
	global_store_dword v[116:117], v114, off
.LBB0_236:
	s_or_b64 exec, exec, s[50:51]
	v_lshl_add_u64 v[184:185], v[184:185], 0, v[188:189]
	global_load_dwordx4 v[168:171], v[184:185], off
	global_load_dwordx4 v[172:175], v[184:185], off offset:16
	global_load_dwordx4 v[176:179], v[184:185], off offset:512
	global_load_dwordx4 v[180:183], v[184:185], off offset:528
	v_add_u32_e32 v114, 16, v142
	s_waitcnt lgkmcnt(0)
	v_ashrrev_i32_e32 v115, 31, v114
	v_lshlrev_b64 v[116:117], 10, v[114:115]
	v_lshl_add_u64 v[120:121], v[116:117], 0, v[140:141]
	v_readlane_b32 s28, v235, 13
	v_lshlrev_b64 v[128:129], 2, v[120:121]
	v_readlane_b32 s29, v235, 14
	v_lshl_add_u64 v[120:121], v[120:121], 1, s[22:23]
	s_nop 0
	v_lshl_add_u64 v[148:149], s[28:29], 0, v[128:129]
	s_nop 0
	s_nop 0
	v_lshl_add_u64 v[128:129], s[70:71], 0, v[128:129]
	s_waitcnt vmcnt(22)
	v_pk_add_f32 v[112:113], v[112:113], v[202:203]
	v_pk_add_f32 v[110:111], v[110:111], v[200:201]
	s_waitcnt vmcnt(21)
	v_pk_add_f32 v[108:109], v[108:109], v[206:207]
	v_pk_add_f32 v[106:107], v[106:107], v[204:205]
	v_cvt_pk_bf16_f32 v116, v110, v111
	v_cvt_pk_bf16_f32 v117, v112, v113
	v_cvt_pk_bf16_f32 v118, v106, v107
	v_cvt_pk_bf16_f32 v119, v108, v109
	global_store_dwordx4 v[128:129], v[110:113], off
	global_store_dwordx4 v[128:129], v[106:109], off offset:16
	global_store_dwordx4 v[120:121], v[116:119], off
	s_nop 0
	s_nop 0
	s_nop 0
	v_mul_f32_e32 v111, v111, v111
	v_mul_f32_e32 v113, v113, v113
	v_mul_f32_e32 v107, v107, v107
	v_mul_f32_e32 v109, v109, v109
	v_fmac_f32_e32 v111, v110, v110
	v_fmac_f32_e32 v113, v112, v112
	v_fmac_f32_e32 v107, v106, v106
	v_fmac_f32_e32 v109, v108, v108
	v_add_f32_e32 v106, v111, v113
	v_add_f32_e32 v107, v107, v109
	v_add_f32_e32 v110, v107, v106
	s_waitcnt vmcnt(23)
	v_pk_add_f32 v[104:105], v[104:105], v[210:211]
	v_pk_add_f32 v[102:103], v[102:103], v[208:209]
	s_waitcnt vmcnt(22)
	v_pk_add_f32 v[108:109], v[100:101], v[214:215]
	v_pk_add_f32 v[106:107], v[98:99], v[212:213]
	v_mul_f32_e32 v98, v103, v103
	v_mul_f32_e32 v99, v105, v105
	v_mul_f32_e32 v100, v107, v107
	v_mul_f32_e32 v101, v109, v109
	v_fmac_f32_e32 v98, v102, v102
	v_fmac_f32_e32 v99, v104, v104
	v_fmac_f32_e32 v100, v106, v106
	v_fmac_f32_e32 v101, v108, v108
	v_add_f32_e32 v98, v98, v99
	v_add_f32_e32 v99, v100, v101
	v_add_f32_e32 v98, v99, v98
	v_add_f32_e32 v98, v110, v98
	ds_bpermute_b32 v99, v123, v98
	global_store_dwordx4 v[128:129], v[102:105], off offset:512
	global_store_dwordx4 v[128:129], v[106:109], off offset:528
	v_cvt_pk_bf16_f32 v100, v102, v103
	v_cvt_pk_bf16_f32 v101, v104, v105
	v_cvt_pk_bf16_f32 v102, v106, v107
	s_waitcnt lgkmcnt(0)
	v_add_f32_e32 v98, v98, v99
	ds_bpermute_b32 v99, v122, v98
	v_cvt_pk_bf16_f32 v103, v108, v109
	global_store_dwordx4 v[120:121], v[100:103], off offset:256
	s_and_saveexec_b64 s[50:51], vcc
	s_cbranch_execz .LBB0_238
	v_readlane_b32 s28, v235, 1
	v_lshlrev_b64 v[100:101], 6, v[114:115]
	v_readlane_b32 s29, v235, 2
	s_lshl_b32 s78, s60, 2
	s_waitcnt lgkmcnt(0)
	v_add_f32_e32 v98, v98, v99
	v_lshl_add_u64 v[100:101], s[28:29], 0, v[100:101]
	v_lshl_add_u64 v[100:101], s[54:55], 2, v[100:101]
	v_lshl_add_u64 v[100:101], v[100:101], 0, s[78:79]
	s_mov_b32 s78, s76
	global_store_dword v[100:101], v98, off
.LBB0_238:
	s_or_b64 exec, exec, s[50:51]
	v_lshl_add_u64 v[184:185], v[184:185], 0, v[186:187]
	global_load_dwordx4 v[200:203], v[184:185], off
	global_load_dwordx4 v[204:207], v[184:185], off offset:16
	global_load_dwordx4 v[208:211], v[184:185], off offset:512
	global_load_dwordx4 v[212:215], v[184:185], off offset:528
	v_add_u32_e32 v98, 32, v142
	s_waitcnt lgkmcnt(0)
	v_ashrrev_i32_e32 v99, 31, v98
	v_lshlrev_b64 v[100:101], 10, v[98:99]
	v_lshl_add_u64 v[108:109], v[100:101], 0, v[140:141]
	v_readlane_b32 s28, v235, 13
	v_lshlrev_b64 v[110:111], 2, v[108:109]
	v_readlane_b32 s29, v235, 14
	v_lshl_add_u64 v[108:109], v[108:109], 1, s[22:23]
	s_nop 0
	v_lshl_add_u64 v[112:113], s[28:29], 0, v[110:111]
	s_nop 0
	s_nop 0
	v_lshl_add_u64 v[110:111], s[70:71], 0, v[110:111]
	s_waitcnt vmcnt(29)
	v_pk_add_f32 v[96:97], v[96:97], v[218:219]
	v_pk_add_f32 v[94:95], v[94:95], v[216:217]
	s_waitcnt vmcnt(28)
	v_pk_add_f32 v[92:93], v[92:93], v[222:223]
	v_pk_add_f32 v[90:91], v[90:91], v[220:221]
	v_cvt_pk_bf16_f32 v100, v94, v95
	v_cvt_pk_bf16_f32 v101, v96, v97
	v_cvt_pk_bf16_f32 v102, v90, v91
	v_cvt_pk_bf16_f32 v103, v92, v93
	global_store_dwordx4 v[110:111], v[94:97], off
	global_store_dwordx4 v[110:111], v[90:93], off offset:16
	global_store_dwordx4 v[108:109], v[100:103], off
	s_nop 0
	s_nop 0
	s_nop 0
	v_mul_f32_e32 v95, v95, v95
	v_mul_f32_e32 v97, v97, v97
	v_mul_f32_e32 v91, v91, v91
	v_mul_f32_e32 v93, v93, v93
	v_fmac_f32_e32 v95, v94, v94
	v_fmac_f32_e32 v97, v96, v96
	v_fmac_f32_e32 v91, v90, v90
	v_fmac_f32_e32 v93, v92, v92
	v_add_f32_e32 v90, v95, v97
	v_add_f32_e32 v91, v91, v93
	v_add_f32_e32 v94, v91, v90
	s_waitcnt vmcnt(30)
	v_pk_add_f32 v[88:89], v[88:89], v[226:227]
	v_pk_add_f32 v[86:87], v[86:87], v[224:225]
	s_waitcnt vmcnt(29)
	v_pk_add_f32 v[92:93], v[84:85], v[230:231]
	v_pk_add_f32 v[90:91], v[82:83], v[228:229]
	v_mul_f32_e32 v82, v87, v87
	v_mul_f32_e32 v83, v89, v89
	v_mul_f32_e32 v84, v91, v91
	v_mul_f32_e32 v85, v93, v93
	v_fmac_f32_e32 v82, v86, v86
	v_fmac_f32_e32 v83, v88, v88
	v_fmac_f32_e32 v84, v90, v90
	v_fmac_f32_e32 v85, v92, v92
	v_add_f32_e32 v82, v82, v83
	v_add_f32_e32 v83, v84, v85
	v_add_f32_e32 v82, v83, v82
	v_add_f32_e32 v82, v94, v82
	ds_bpermute_b32 v83, v123, v82
	global_store_dwordx4 v[110:111], v[86:89], off offset:512
	global_store_dwordx4 v[110:111], v[90:93], off offset:528
	v_cvt_pk_bf16_f32 v84, v86, v87
	v_cvt_pk_bf16_f32 v85, v88, v89
	v_cvt_pk_bf16_f32 v86, v90, v91
	s_waitcnt lgkmcnt(0)
	v_add_f32_e32 v82, v82, v83
	ds_bpermute_b32 v83, v122, v82
	v_cvt_pk_bf16_f32 v87, v92, v93
	global_store_dwordx4 v[108:109], v[84:87], off offset:256
	s_and_saveexec_b64 s[50:51], vcc
	s_cbranch_execz .LBB0_240
	v_readlane_b32 s28, v235, 1
	v_lshlrev_b64 v[84:85], 6, v[98:99]
	v_readlane_b32 s29, v235, 2
	s_lshl_b32 s78, s60, 2
	s_waitcnt lgkmcnt(0)
	v_add_f32_e32 v82, v82, v83
	v_lshl_add_u64 v[84:85], s[28:29], 0, v[84:85]
	v_lshl_add_u64 v[84:85], s[54:55], 2, v[84:85]
	v_lshl_add_u64 v[84:85], v[84:85], 0, s[78:79]
	s_mov_b32 s78, s76
	global_store_dword v[84:85], v82, off
.LBB0_240:
	s_or_b64 exec, exec, s[50:51]
	v_lshl_add_u64 v[184:185], v[184:185], 0, v[186:187]
	global_load_dwordx4 v[216:219], v[184:185], off
	global_load_dwordx4 v[220:223], v[184:185], off offset:16
	global_load_dwordx4 v[224:227], v[184:185], off offset:512
	global_load_dwordx4 v[228:231], v[184:185], off offset:528
	v_add_u32_e32 v82, 48, v142
	s_waitcnt lgkmcnt(0)
	v_ashrrev_i32_e32 v83, 31, v82
	v_lshlrev_b64 v[84:85], 10, v[82:83]
	v_lshl_add_u64 v[92:93], v[84:85], 0, v[140:141]
	v_readlane_b32 s28, v235, 13
	v_lshlrev_b64 v[94:95], 2, v[92:93]
	v_readlane_b32 s29, v235, 14
	v_lshl_add_u64 v[92:93], v[92:93], 1, s[22:23]
	s_nop 0
	v_lshl_add_u64 v[96:97], s[28:29], 0, v[94:95]
	s_nop 0
	s_nop 0
	v_lshl_add_u64 v[94:95], s[70:71], 0, v[94:95]
	s_waitcnt vmcnt(36)
	v_pk_add_f32 v[80:81], v[80:81], v[240:241]
	v_pk_add_f32 v[78:79], v[78:79], v[238:239]
	s_waitcnt vmcnt(35)
	v_pk_add_f32 v[76:77], v[76:77], v[244:245]
	v_pk_add_f32 v[74:75], v[74:75], v[242:243]
	v_cvt_pk_bf16_f32 v84, v78, v79
	v_cvt_pk_bf16_f32 v85, v80, v81
	v_cvt_pk_bf16_f32 v86, v74, v75
	v_cvt_pk_bf16_f32 v87, v76, v77
	global_store_dwordx4 v[94:95], v[78:81], off
	global_store_dwordx4 v[94:95], v[74:77], off offset:16
	global_store_dwordx4 v[92:93], v[84:87], off
	s_nop 0
	s_nop 0
	s_nop 0
	v_mul_f32_e32 v79, v79, v79
	v_mul_f32_e32 v81, v81, v81
	v_mul_f32_e32 v75, v75, v75
	v_mul_f32_e32 v77, v77, v77
	v_fmac_f32_e32 v79, v78, v78
	v_fmac_f32_e32 v81, v80, v80
	v_fmac_f32_e32 v75, v74, v74
	v_fmac_f32_e32 v77, v76, v76
	v_add_f32_e32 v74, v79, v81
	v_add_f32_e32 v75, v75, v77
	v_add_f32_e32 v78, v75, v74
	s_waitcnt vmcnt(37)
	v_pk_add_f32 v[72:73], v[72:73], v[248:249]
	v_pk_add_f32 v[70:71], v[70:71], v[246:247]
	s_waitcnt vmcnt(36)
	v_pk_add_f32 v[76:77], v[68:69], v[252:253]
	v_pk_add_f32 v[74:75], v[66:67], v[250:251]
	v_mul_f32_e32 v66, v71, v71
	v_mul_f32_e32 v67, v73, v73
	v_mul_f32_e32 v68, v75, v75
	v_mul_f32_e32 v69, v77, v77
	v_fmac_f32_e32 v66, v70, v70
	v_fmac_f32_e32 v67, v72, v72
	v_fmac_f32_e32 v68, v74, v74
	v_fmac_f32_e32 v69, v76, v76
	v_add_f32_e32 v66, v66, v67
	v_add_f32_e32 v67, v68, v69
	v_add_f32_e32 v66, v67, v66
	v_add_f32_e32 v66, v78, v66
	ds_bpermute_b32 v67, v123, v66
	global_store_dwordx4 v[94:95], v[70:73], off offset:512
	global_store_dwordx4 v[94:95], v[74:77], off offset:528
	v_cvt_pk_bf16_f32 v68, v70, v71
	v_cvt_pk_bf16_f32 v69, v72, v73
	v_cvt_pk_bf16_f32 v70, v74, v75
	s_waitcnt lgkmcnt(0)
	v_add_f32_e32 v66, v66, v67
	ds_bpermute_b32 v67, v122, v66
	v_cvt_pk_bf16_f32 v71, v76, v77
	global_store_dwordx4 v[92:93], v[68:71], off offset:256
	s_and_saveexec_b64 s[50:51], vcc
	s_cbranch_execz .LBB0_242
	v_readlane_b32 s28, v235, 1
	v_lshlrev_b64 v[68:69], 6, v[82:83]
	v_readlane_b32 s29, v235, 2
	s_lshl_b32 s78, s60, 2
	s_waitcnt lgkmcnt(0)
	v_add_f32_e32 v66, v66, v67
	v_lshl_add_u64 v[68:69], s[28:29], 0, v[68:69]
	v_lshl_add_u64 v[68:69], s[54:55], 2, v[68:69]
	v_lshl_add_u64 v[68:69], v[68:69], 0, s[78:79]
	s_mov_b32 s78, s76
	global_store_dword v[68:69], v66, off
.LBB0_242:
	s_or_b64 exec, exec, s[50:51]
	v_lshl_add_u64 v[184:185], v[184:185], 0, v[186:187]
	global_load_dwordx4 v[238:241], v[184:185], off
	global_load_dwordx4 v[242:245], v[184:185], off offset:16
	global_load_dwordx4 v[246:249], v[184:185], off offset:512
	global_load_dwordx4 v[250:253], v[184:185], off offset:528
	v_add_u32_e32 v66, 0x80, v142
	s_waitcnt lgkmcnt(0)
	v_ashrrev_i32_e32 v67, 31, v66
	v_lshlrev_b64 v[68:69], 10, v[66:67]
	v_lshl_add_u64 v[76:77], v[68:69], 0, v[140:141]
	v_readlane_b32 s28, v235, 13
	v_lshlrev_b64 v[78:79], 2, v[76:77]
	v_readlane_b32 s29, v235, 14
	v_lshl_add_u64 v[76:77], v[76:77], 1, s[22:23]
	s_nop 0
	v_lshl_add_u64 v[80:81], s[28:29], 0, v[78:79]
	s_nop 0
	s_nop 0
	v_lshl_add_u64 v[78:79], s[70:71], 0, v[78:79]
	s_waitcnt vmcnt(36)
	v_pk_add_f32 v[64:65], v[64:65], v[170:171]
	v_pk_add_f32 v[62:63], v[62:63], v[168:169]
	s_waitcnt vmcnt(35)
	v_pk_add_f32 v[60:61], v[60:61], v[174:175]
	v_pk_add_f32 v[58:59], v[58:59], v[172:173]
	v_cvt_pk_bf16_f32 v68, v62, v63
	v_cvt_pk_bf16_f32 v69, v64, v65
	v_cvt_pk_bf16_f32 v70, v58, v59
	v_cvt_pk_bf16_f32 v71, v60, v61
	global_store_dwordx4 v[78:79], v[62:65], off
	global_store_dwordx4 v[78:79], v[58:61], off offset:16
	global_store_dwordx4 v[76:77], v[68:71], off
	s_nop 0
	s_nop 0
	s_nop 0
	v_mul_f32_e32 v63, v63, v63
	v_mul_f32_e32 v65, v65, v65
	v_mul_f32_e32 v59, v59, v59
	v_mul_f32_e32 v61, v61, v61
	v_fmac_f32_e32 v63, v62, v62
	v_fmac_f32_e32 v65, v64, v64
	v_fmac_f32_e32 v59, v58, v58
	v_fmac_f32_e32 v61, v60, v60
	v_add_f32_e32 v58, v63, v65
	v_add_f32_e32 v59, v59, v61
	v_add_f32_e32 v62, v59, v58
	s_waitcnt vmcnt(37)
	v_pk_add_f32 v[56:57], v[56:57], v[178:179]
	v_pk_add_f32 v[54:55], v[54:55], v[176:177]
	s_waitcnt vmcnt(36)
	v_pk_add_f32 v[60:61], v[52:53], v[182:183]
	v_pk_add_f32 v[58:59], v[50:51], v[180:181]
	v_mul_f32_e32 v50, v55, v55
	v_mul_f32_e32 v51, v57, v57
	v_mul_f32_e32 v52, v59, v59
	v_mul_f32_e32 v53, v61, v61
	v_fmac_f32_e32 v50, v54, v54
	v_fmac_f32_e32 v51, v56, v56
	v_fmac_f32_e32 v52, v58, v58
	v_fmac_f32_e32 v53, v60, v60
	v_add_f32_e32 v50, v50, v51
	v_add_f32_e32 v51, v52, v53
	v_add_f32_e32 v50, v51, v50
	v_add_f32_e32 v50, v62, v50
	ds_bpermute_b32 v51, v123, v50
	global_store_dwordx4 v[78:79], v[54:57], off offset:512
	global_store_dwordx4 v[78:79], v[58:61], off offset:528
	v_cvt_pk_bf16_f32 v52, v54, v55
	v_cvt_pk_bf16_f32 v53, v56, v57
	v_cvt_pk_bf16_f32 v54, v58, v59
	s_waitcnt lgkmcnt(0)
	v_add_f32_e32 v50, v50, v51
	ds_bpermute_b32 v51, v122, v50
	v_cvt_pk_bf16_f32 v55, v60, v61
	global_store_dwordx4 v[76:77], v[52:55], off offset:256
	s_and_saveexec_b64 s[50:51], vcc
	s_cbranch_execz .LBB0_244
	v_readlane_b32 s28, v235, 1
	v_lshlrev_b64 v[52:53], 6, v[66:67]
	v_readlane_b32 s29, v235, 2
	s_lshl_b32 s78, s60, 2
	s_waitcnt lgkmcnt(0)
	v_add_f32_e32 v50, v50, v51
	v_lshl_add_u64 v[52:53], s[28:29], 0, v[52:53]
	v_lshl_add_u64 v[52:53], s[54:55], 2, v[52:53]
	v_lshl_add_u64 v[52:53], v[52:53], 0, s[78:79]
	s_mov_b32 s78, s76
	global_store_dword v[52:53], v50, off
.LBB0_244:
	s_or_b64 exec, exec, s[50:51]
	v_add_u32_e32 v50, 0x90, v142
	s_waitcnt lgkmcnt(0)
	v_ashrrev_i32_e32 v51, 31, v50
	v_lshlrev_b64 v[52:53], 10, v[50:51]
	v_lshl_add_u64 v[60:61], v[52:53], 0, v[140:141]
	v_readlane_b32 s28, v235, 13
	v_lshlrev_b64 v[62:63], 2, v[60:61]
	v_readlane_b32 s29, v235, 14
	v_lshl_add_u64 v[60:61], v[60:61], 1, s[22:23]
	s_nop 0
	v_lshl_add_u64 v[64:65], s[28:29], 0, v[62:63]
	s_nop 0
	s_nop 0
	v_lshl_add_u64 v[62:63], s[70:71], 0, v[62:63]
	s_waitcnt vmcnt(32)
	v_pk_add_f32 v[48:49], v[48:49], v[202:203]
	v_pk_add_f32 v[46:47], v[46:47], v[200:201]
	s_waitcnt vmcnt(31)
	v_pk_add_f32 v[44:45], v[44:45], v[206:207]
	v_pk_add_f32 v[42:43], v[42:43], v[204:205]
	v_cvt_pk_bf16_f32 v52, v46, v47
	v_cvt_pk_bf16_f32 v53, v48, v49
	v_cvt_pk_bf16_f32 v54, v42, v43
	v_cvt_pk_bf16_f32 v55, v44, v45
	global_store_dwordx4 v[62:63], v[46:49], off
	global_store_dwordx4 v[62:63], v[42:45], off offset:16
	global_store_dwordx4 v[60:61], v[52:55], off
	s_nop 0
	s_nop 0
	s_nop 0
	v_mul_f32_e32 v47, v47, v47
	v_mul_f32_e32 v49, v49, v49
	v_mul_f32_e32 v43, v43, v43
	v_mul_f32_e32 v45, v45, v45
	v_fmac_f32_e32 v47, v46, v46
	v_fmac_f32_e32 v49, v48, v48
	v_fmac_f32_e32 v43, v42, v42
	v_fmac_f32_e32 v45, v44, v44
	v_add_f32_e32 v42, v47, v49
	v_add_f32_e32 v43, v43, v45
	v_add_f32_e32 v46, v43, v42
	s_waitcnt vmcnt(33)
	v_pk_add_f32 v[40:41], v[40:41], v[210:211]
	v_pk_add_f32 v[38:39], v[38:39], v[208:209]
	s_waitcnt vmcnt(32)
	v_pk_add_f32 v[44:45], v[36:37], v[214:215]
	v_pk_add_f32 v[42:43], v[34:35], v[212:213]
	v_mul_f32_e32 v34, v39, v39
	v_mul_f32_e32 v35, v41, v41
	v_mul_f32_e32 v36, v43, v43
	v_mul_f32_e32 v37, v45, v45
	v_fmac_f32_e32 v34, v38, v38
	v_fmac_f32_e32 v35, v40, v40
	v_fmac_f32_e32 v36, v42, v42
	v_fmac_f32_e32 v37, v44, v44
	v_add_f32_e32 v34, v34, v35
	v_add_f32_e32 v35, v36, v37
	v_add_f32_e32 v34, v35, v34
	v_add_f32_e32 v34, v46, v34
	ds_bpermute_b32 v35, v123, v34
	global_store_dwordx4 v[62:63], v[38:41], off offset:512
	global_store_dwordx4 v[62:63], v[42:45], off offset:528
	v_cvt_pk_bf16_f32 v36, v38, v39
	v_cvt_pk_bf16_f32 v37, v40, v41
	v_cvt_pk_bf16_f32 v38, v42, v43
	s_waitcnt lgkmcnt(0)
	v_add_f32_e32 v34, v34, v35
	ds_bpermute_b32 v35, v122, v34
	v_cvt_pk_bf16_f32 v39, v44, v45
	global_store_dwordx4 v[60:61], v[36:39], off offset:256
	s_and_saveexec_b64 s[50:51], vcc
	s_cbranch_execz .LBB0_246
	v_readlane_b32 s28, v235, 1
	v_lshlrev_b64 v[36:37], 6, v[50:51]
	v_readlane_b32 s29, v235, 2
	s_lshl_b32 s78, s60, 2
	s_waitcnt lgkmcnt(0)
	v_add_f32_e32 v34, v34, v35
	v_lshl_add_u64 v[36:37], s[28:29], 0, v[36:37]
	v_lshl_add_u64 v[36:37], s[54:55], 2, v[36:37]
	v_lshl_add_u64 v[36:37], v[36:37], 0, s[78:79]
	s_mov_b32 s78, s76
	global_store_dword v[36:37], v34, off
.LBB0_246:
	s_or_b64 exec, exec, s[50:51]
	v_add_u32_e32 v34, 0xa0, v142
	s_waitcnt lgkmcnt(0)
	v_ashrrev_i32_e32 v35, 31, v34
	v_lshlrev_b64 v[36:37], 10, v[34:35]
	v_lshl_add_u64 v[44:45], v[36:37], 0, v[140:141]
	v_readlane_b32 s28, v235, 13
	v_lshlrev_b64 v[46:47], 2, v[44:45]
	v_readlane_b32 s29, v235, 14
	v_lshl_add_u64 v[44:45], v[44:45], 1, s[22:23]
	s_nop 0
	v_lshl_add_u64 v[48:49], s[28:29], 0, v[46:47]
	s_nop 0
	s_nop 0
	v_lshl_add_u64 v[46:47], s[70:71], 0, v[46:47]
	s_waitcnt vmcnt(28)
	v_pk_add_f32 v[32:33], v[32:33], v[218:219]
	v_pk_add_f32 v[30:31], v[30:31], v[216:217]
	s_waitcnt vmcnt(27)
	v_pk_add_f32 v[28:29], v[28:29], v[222:223]
	v_pk_add_f32 v[26:27], v[26:27], v[220:221]
	v_cvt_pk_bf16_f32 v36, v30, v31
	v_cvt_pk_bf16_f32 v37, v32, v33
	v_cvt_pk_bf16_f32 v38, v26, v27
	v_cvt_pk_bf16_f32 v39, v28, v29
	global_store_dwordx4 v[46:47], v[30:33], off
	global_store_dwordx4 v[46:47], v[26:29], off offset:16
	global_store_dwordx4 v[44:45], v[36:39], off
	s_nop 0
	s_nop 0
	s_nop 0
	v_mul_f32_e32 v31, v31, v31
	v_mul_f32_e32 v33, v33, v33
	v_mul_f32_e32 v27, v27, v27
	v_mul_f32_e32 v29, v29, v29
	v_fmac_f32_e32 v31, v30, v30
	v_fmac_f32_e32 v33, v32, v32
	v_fmac_f32_e32 v27, v26, v26
	v_fmac_f32_e32 v29, v28, v28
	v_add_f32_e32 v26, v31, v33
	v_add_f32_e32 v27, v27, v29
	v_add_f32_e32 v30, v27, v26
	s_waitcnt vmcnt(29)
	v_pk_add_f32 v[24:25], v[24:25], v[226:227]
	v_pk_add_f32 v[22:23], v[22:23], v[224:225]
	s_waitcnt vmcnt(28)
	v_pk_add_f32 v[28:29], v[20:21], v[230:231]
	v_pk_add_f32 v[26:27], v[18:19], v[228:229]
	v_mul_f32_e32 v18, v23, v23
	v_mul_f32_e32 v19, v25, v25
	v_mul_f32_e32 v20, v27, v27
	v_mul_f32_e32 v21, v29, v29
	v_fmac_f32_e32 v18, v22, v22
	v_fmac_f32_e32 v19, v24, v24
	v_fmac_f32_e32 v20, v26, v26
	v_fmac_f32_e32 v21, v28, v28
	v_add_f32_e32 v18, v18, v19
	v_add_f32_e32 v19, v20, v21
	v_add_f32_e32 v18, v19, v18
	v_add_f32_e32 v18, v30, v18
	ds_bpermute_b32 v19, v123, v18
	global_store_dwordx4 v[46:47], v[22:25], off offset:512
	global_store_dwordx4 v[46:47], v[26:29], off offset:528
	v_cvt_pk_bf16_f32 v20, v22, v23
	v_cvt_pk_bf16_f32 v21, v24, v25
	v_cvt_pk_bf16_f32 v22, v26, v27
	s_waitcnt lgkmcnt(0)
	v_add_f32_e32 v18, v18, v19
	ds_bpermute_b32 v19, v122, v18
	v_cvt_pk_bf16_f32 v23, v28, v29
	global_store_dwordx4 v[44:45], v[20:23], off offset:256
	s_and_saveexec_b64 s[50:51], vcc
	s_cbranch_execz .LBB0_248
	v_readlane_b32 s28, v235, 1
	v_lshlrev_b64 v[20:21], 6, v[34:35]
	v_readlane_b32 s29, v235, 2
	s_lshl_b32 s78, s60, 2
	s_waitcnt lgkmcnt(0)
	v_add_f32_e32 v18, v18, v19
	v_lshl_add_u64 v[20:21], s[28:29], 0, v[20:21]
	v_lshl_add_u64 v[20:21], s[54:55], 2, v[20:21]
	v_lshl_add_u64 v[20:21], v[20:21], 0, s[78:79]
	s_mov_b32 s78, s76
	global_store_dword v[20:21], v18, off
.LBB0_248:
	s_or_b64 exec, exec, s[50:51]
	v_add_u32_e32 v18, 0xb0, v142
	s_waitcnt lgkmcnt(0)
	v_ashrrev_i32_e32 v19, 31, v18
	v_lshlrev_b64 v[20:21], 10, v[18:19]
	v_lshl_add_u64 v[28:29], v[20:21], 0, v[140:141]
	v_readlane_b32 s28, v235, 13
	v_lshlrev_b64 v[30:31], 2, v[28:29]
	v_readlane_b32 s29, v235, 14
	v_lshl_add_u64 v[28:29], v[28:29], 1, s[22:23]
	s_nop 0
	v_lshl_add_u64 v[32:33], s[28:29], 0, v[30:31]
	s_nop 0
	s_nop 0
	v_lshl_add_u64 v[30:31], s[70:71], 0, v[30:31]
	s_waitcnt vmcnt(24)
	v_pk_add_f32 v[16:17], v[16:17], v[240:241]
	v_pk_add_f32 v[14:15], v[14:15], v[238:239]
	s_waitcnt vmcnt(23)
	v_pk_add_f32 v[12:13], v[12:13], v[244:245]
	v_pk_add_f32 v[10:11], v[10:11], v[242:243]
	v_cvt_pk_bf16_f32 v20, v14, v15
	v_cvt_pk_bf16_f32 v21, v16, v17
	v_cvt_pk_bf16_f32 v22, v10, v11
	v_cvt_pk_bf16_f32 v23, v12, v13
	global_store_dwordx4 v[30:31], v[14:17], off
	global_store_dwordx4 v[30:31], v[10:13], off offset:16
	global_store_dwordx4 v[28:29], v[20:23], off
	s_nop 0
	s_nop 0
	s_nop 0
	v_mul_f32_e32 v15, v15, v15
	v_mul_f32_e32 v17, v17, v17
	v_mul_f32_e32 v11, v11, v11
	v_mul_f32_e32 v13, v13, v13
	v_fmac_f32_e32 v15, v14, v14
	v_fmac_f32_e32 v17, v16, v16
	v_fmac_f32_e32 v11, v10, v10
	v_fmac_f32_e32 v13, v12, v12
	v_add_f32_e32 v10, v15, v17
	v_add_f32_e32 v11, v11, v13
	v_add_f32_e32 v14, v11, v10
	s_waitcnt vmcnt(25)
	v_pk_add_f32 v[8:9], v[8:9], v[248:249]
	v_pk_add_f32 v[6:7], v[6:7], v[246:247]
	s_waitcnt vmcnt(24)
	v_pk_add_f32 v[12:13], v[4:5], v[252:253]
	v_pk_add_f32 v[10:11], v[2:3], v[250:251]
	v_mul_f32_e32 v2, v7, v7
	v_mul_f32_e32 v3, v9, v9
	v_mul_f32_e32 v4, v11, v11
	v_mul_f32_e32 v5, v13, v13
	v_fmac_f32_e32 v2, v6, v6
	v_fmac_f32_e32 v3, v8, v8
	v_fmac_f32_e32 v4, v10, v10
	v_fmac_f32_e32 v5, v12, v12
	v_add_f32_e32 v2, v2, v3
	v_add_f32_e32 v3, v4, v5
	v_add_f32_e32 v2, v3, v2
	v_add_f32_e32 v2, v14, v2
	ds_bpermute_b32 v3, v123, v2
	global_store_dwordx4 v[30:31], v[6:9], off offset:512
	global_store_dwordx4 v[30:31], v[10:13], off offset:528
	v_cvt_pk_bf16_f32 v4, v6, v7
	v_cvt_pk_bf16_f32 v5, v8, v9
	v_cvt_pk_bf16_f32 v6, v10, v11
	s_waitcnt lgkmcnt(0)
	v_add_f32_e32 v2, v2, v3
	ds_bpermute_b32 v3, v122, v2
	v_cvt_pk_bf16_f32 v7, v12, v13
	global_store_dwordx4 v[28:29], v[4:7], off offset:256
	s_and_saveexec_b64 s[50:51], vcc
	s_cbranch_execz .LBB0_250
	v_readlane_b32 s28, v235, 1
	v_lshlrev_b64 v[4:5], 6, v[18:19]
	v_readlane_b32 s29, v235, 2
	s_lshl_b32 s78, s60, 2
	s_waitcnt lgkmcnt(0)
	v_add_f32_e32 v2, v2, v3
	v_lshl_add_u64 v[4:5], s[28:29], 0, v[4:5]
	v_lshl_add_u64 v[4:5], s[54:55], 2, v[4:5]
	v_lshl_add_u64 v[4:5], v[4:5], 0, s[78:79]
	s_mov_b32 s78, s76
	global_store_dword v[4:5], v2, off

	.amdhsa_kernel _Z10fwd_kernel4Args
		.amdhsa_group_segment_fixed_size 0
		.amdhsa_private_segment_fixed_size 0
		.amdhsa_kernarg_size 400
		.amdhsa_user_sgpr_count 2
		.amdhsa_user_sgpr_dispatch_ptr 0
		.amdhsa_user_sgpr_queue_ptr 0
		.amdhsa_user_sgpr_kernarg_segment_ptr 1
		.amdhsa_user_sgpr_dispatch_id 0
		.amdhsa_user_sgpr_kernarg_preload_length 0
		.amdhsa_user_sgpr_kernarg_preload_offset 0
		.amdhsa_user_sgpr_private_segment_size 0
		.amdhsa_uses_dynamic_stack 0
		.amdhsa_enable_private_segment 0
		.amdhsa_system_sgpr_workgroup_id_x 1
		.amdhsa_system_sgpr_workgroup_id_y 0
		.amdhsa_system_sgpr_workgroup_id_z 0
		.amdhsa_system_sgpr_workgroup_info 0
		.amdhsa_system_vgpr_workitem_id 2
		.amdhsa_next_free_vgpr 254
		.amdhsa_next_free_sgpr 102
		.amdhsa_accum_offset 256
		.amdhsa_reserve_vcc 1
		.amdhsa_float_round_mode_32 0
		.amdhsa_float_round_mode_16_64 0
		.amdhsa_float_denorm_mode_32 3
		.amdhsa_float_denorm_mode_16_64 3
		.amdhsa_dx10_clamp 1
		.amdhsa_ieee_mode 1
		.amdhsa_fp16_overflow 0
		.amdhsa_tg_split 0
		.amdhsa_exception_fp_ieee_invalid_op 0
		.amdhsa_exception_fp_denorm_src 0
		.amdhsa_exception_fp_ieee_div_zero 0
		.amdhsa_exception_fp_ieee_overflow 0
		.amdhsa_exception_fp_ieee_underflow 0
		.amdhsa_exception_fp_ieee_inexact 0
		.amdhsa_exception_int_div_zero 0
	.end_amdhsa_kernel

amdhsa.kernels:
  - .agpr_count:     0
    .args:
      - .offset:         0
        .size:           144
        .value_kind:     by_value
      - .offset:         144
        .size:           4
        .value_kind:     hidden_block_count_x
      - .offset:         148
        .size:           4
        .value_kind:     hidden_block_count_y
      - .offset:         152
        .size:           4
        .value_kind:     hidden_block_count_z
      - .offset:         156
        .size:           2
        .value_kind:     hidden_group_size_x
      - .offset:         158
        .size:           2
        .value_kind:     hidden_group_size_y
      - .offset:         160
        .size:           2
        .value_kind:     hidden_group_size_z
      - .offset:         162
        .size:           2
        .value_kind:     hidden_remainder_x
      - .offset:         164
        .size:           2
        .value_kind:     hidden_remainder_y
      - .offset:         166
        .size:           2
        .value_kind:     hidden_remainder_z
      - .offset:         184
        .size:           8
        .value_kind:     hidden_global_offset_x
      - .offset:         192
        .size:           8
        .value_kind:     hidden_global_offset_y
      - .offset:         200
        .size:           8
        .value_kind:     hidden_global_offset_z
      - .offset:         208
        .size:           2
        .value_kind:     hidden_grid_dims
      - .offset:         232
        .size:           8
        .value_kind:     hidden_multigrid_sync_arg
      - .offset:         264
        .size:           4
        .value_kind:     hidden_dynamic_lds_size
    .group_segment_fixed_size: 0
    .kernarg_segment_align: 8
    .kernarg_segment_size: 400
    .language:       OpenCL C
    .language_version:
      - 2
      - 0
    .max_flat_workgroup_size: 512
    .name:           _Z10fwd_kernel4Args
    .private_segment_fixed_size: 0
    .sgpr_count:     108
    .sgpr_spill_count: 216
    .symbol:         _Z10fwd_kernel4Args.kd
    .uniform_work_group_size: 1
    .uses_dynamic_stack: false
    .vgpr_count:     254
    .vgpr_spill_count: 0
    .wavefront_size: 64
